# wp + next item's fast-path loads issued at the start of pass 2 (under its LDS reads) instead of its end
# baseline (speedup 1.0000x reference)
.LBB0_293:
	s_or_b64 exec, exec, s[4:5]
	v_and_b32_e32 v26, 64, v0
	s_and_b64 s[0:1], s[0:1], exec
	v_cmp_eq_u32_e32 vcc, 0, v26
	v_mov_b32_e32 v26, s69
	v_mov_b32_e32 v27, s67
	v_cndmask_b32_e32 v27, v26, v27, vcc
	v_mov_b32_e32 v26, s68
	v_mov_b32_e32 v28, s66
	s_movk_i32 s0, 0x100
	v_cndmask_b32_e32 v26, v26, v28, vcc
	v_cmp_gt_u32_e64 s[2:3], s0, v0
	v_mov_b32_e32 v28, 0x880
	v_mov_b32_e32 v46, 0x800
	v_lshrrev_b32_e32 v170, 1, v0
	v_and_b32_e32 v1, 63, v0
	v_writelane_b32 v250, s2, 21
	s_cselect_b32 s72, 17, 15
	s_add_u32 s88, s96, 0x2000000
	v_cndmask_b32_e64 v28, v28, v46, s[2:3]
	v_and_b32_e32 v46, 64, v170
	v_or3_b32 v28, v28, v46, v1
	v_lshlrev_b32_e32 v28, 2, v28
	v_lshl_add_u64 v[26:27], v[26:27], 0, v[28:29]
	global_load_dword v26, v[26:27], off
	s_addc_u32 s89, s97, 0
	s_add_i32 s0, 0, 0x24000
	s_lshl_b32 s55, s50, 4
	s_cmpk_gt_u32 s51, 0xff
	s_cselect_b64 s[4:5], -1, 0
	s_cmpk_lt_u32 s51, 0x100
	s_cselect_b64 vcc, -1, 0
	v_writelane_b32 v250, s3, 22
	s_and_b64 s[2:3], vcc, exec
	s_cselect_b32 s3, s45, s47
	s_cselect_b32 s2, s44, s46
	v_and_b32_e32 v110, 48, v0
	v_mov_b32_e32 v111, v29
	v_lshl_add_u32 v27, v0, 2, s0
	v_lshl_add_u64 v[112:113], s[2:3], 0, v[110:111]
	s_movk_i32 s2, 0x340
	v_cmp_gt_u32_e64 s[2:3], s2, v0
	v_bfe_u32 v171, v0, 4, 2
	s_mov_b32 s23, 0x1dc00
	v_writelane_b32 v250, s2, 23
	v_and_b32_e32 v166, 15, v0
	v_lshlrev_b32_e32 v173, 2, v171
	v_writelane_b32 v250, s3, 24
	s_mov_b32 s3, 0xd000
	s_cselect_b32 s2, 0, 0x4000
	s_cselect_b32 s22, s3, 0xf800
	v_or_b32_e32 v54, 16, v166
	v_or_b32_e32 v51, 32, v166
	v_bitop3_b32 v28, s50, v171, 3 bitop3:0x6c
	s_movk_i32 s73, 0xa0
	v_or_b32_e32 v49, 48, v1
	v_lshlrev_b32_e32 v48, 6, v28
	v_lshlrev_b32_e32 v28, 2, v166
	v_mul_u32_u24_e32 v46, 0xa0, v49
	v_lshlrev_b32_e32 v188, 2, v1
	v_and_b32_e32 v72, 4, v173
	v_lshrrev_b32_e32 v111, 3, v0
	v_or_b32_e32 v184, s55, v166
	v_mul_lo_u32 v185, v184, s73
	v_lshlrev_b32_e32 v172, 3, v171
	v_lshlrev_b32_e32 v61, 1, v166
	v_lshl_add_u32 v63, v166, 6, 0
	s_mov_b32 s1, 0
	v_and_or_b32 v176, s55, 48, v166
	v_or_b32_e32 v177, 0x200, v0
	v_or_b32_e32 v178, 0x400, v0
	v_or_b32_e32 v179, 0x600, v0
	v_mul_u32_u24_e32 v167, 0xa0, v166
	v_add_u32_e32 v205, 0x24800, v175
	v_lshrrev_b32_e32 v187, 6, v0
	v_add_u32_e32 v215, v63, v110
	v_mov_b32_e32 v220, 0x90
	v_mov_b32_e32 v138, 0
	s_waitcnt vmcnt(0)
	ds_write_b32 v27, v26
	v_and_b32_e32 v27, 7, v0
	v_lshl_add_u32 v180, v27, 5, s0
	s_mov_b32 s0, 0x8000
	s_cselect_b32 s0, s0, 0xa800
	s_add_i32 s0, s0, 0
	v_add_u32_e32 v181, s0, v110
	s_add_i32 s0, s2, 0
	v_lshl_add_u32 v47, v171, 10, s0
	s_lshl_b32 s0, s50, 8
	s_lshl_b32 s92, s50, 1
	s_add_i32 s0, s0, 0
	s_cmp_lt_u32 s51, 64
	s_cselect_b64 s[8:9], -1, 0
	s_cmpk_gt_u32 s51, 0x7f
	s_cselect_b64 s[10:11], -1, 0
	s_cmpk_gt_u32 s51, 0xbf
	s_cselect_b64 s[12:13], -1, 0
	s_cmpk_gt_u32 s51, 0x13f
	s_cselect_b64 s[14:15], -1, 0
	s_cmpk_gt_u32 s51, 0x17f
	s_cselect_b64 s[16:17], -1, 0
	s_cmpk_gt_u32 s51, 0x1bf
	s_cselect_b64 s[18:19], -1, 0
	s_cmpk_gt_u32 s51, 0x1ff
	v_writelane_b32 v250, s0, 25
	s_cselect_b64 s[20:21], -1, 0
	s_lshr_b32 s0, s51, 7
	s_cmp_eq_u32 s0, 2
	s_cselect_b64 s[2:3], -1, 0
	s_and_b64 s[6:7], s[2:3], exec
	s_cselect_b32 s6, s23, 0x20400
	s_cmp_lg_u32 s0, 1
	s_cselect_b32 s23, s6, 0x4000
	s_cmpk_lt_u32 s51, 0x80
	s_cselect_b64 s[24:25], -1, 0
	s_and_b64 s[6:7], s[24:25], exec
	s_cselect_b32 s6, 0, s23
	v_writelane_b32 v250, s24, 26
	s_or_b64 s[2:3], s[24:25], s[2:3]
	s_mov_b32 s7, 0x14800
	s_and_b64 s[2:3], s[2:3], exec
	s_cselect_b32 s7, s7, 0x12000
	s_bfe_u32 s54, s51, 0x10006
	s_bitcmp1_b32 s51, 6
	s_cselect_b64 s[2:3], -1, 0
	s_add_i32 s22, s22, 0
	v_writelane_b32 v250, s25, 27
	v_mov_b32_e32 v53, s22
	v_cmp_lt_u32_e64 s[22:23], v173, v166
	v_cmp_le_u32_e64 s[24:25], v173, v166
	s_add_i32 s7, s7, 0
	v_cndmask_b32_e64 v56, 0, 1, s[22:23]
	v_cndmask_b32_e64 v57, 0, 1, s[24:25]
	v_cndmask_b32_e32 v56, v57, v56, vcc
	v_and_b32_e32 v56, 1, v56
	v_cmp_eq_u32_e64 s[22:23], 1, v56
	v_or_b32_e32 v56, 17, v173
	v_cmp_lt_u32_e64 s[24:25], v56, v54
	v_cmp_le_u32_e64 s[26:27], v56, v54
	s_add_i32 s6, s6, 0
	v_cndmask_b32_e64 v56, 0, 1, s[24:25]
	v_cndmask_b32_e64 v57, 0, 1, s[26:27]
	v_cndmask_b32_e32 v56, v57, v56, vcc
	v_and_b32_e32 v56, 1, v56
	v_mov_b32_e32 v52, s7
	v_mov_b32_e32 v55, s6
	v_cmp_eq_u32_e64 s[6:7], 1, v56
	v_or_b32_e32 v56, 18, v173
	v_cmp_lt_u32_e64 s[26:27], v56, v54
	v_cmp_le_u32_e64 s[28:29], v56, v54
	v_writelane_b32 v250, s6, 28
	v_cndmask_b32_e64 v56, 0, 1, s[26:27]
	v_cndmask_b32_e64 v57, 0, 1, s[28:29]
	v_cndmask_b32_e32 v56, v57, v56, vcc
	v_and_b32_e32 v56, 1, v56
	v_writelane_b32 v250, s7, 29
	v_cmp_eq_u32_e64 s[6:7], 1, v56
	v_or_b32_e32 v56, 19, v173
	v_cmp_lt_u32_e64 s[28:29], v56, v54
	v_cmp_le_u32_e64 s[30:31], v56, v54
	v_writelane_b32 v250, s6, 30
	v_cndmask_b32_e64 v54, 0, 1, s[28:29]
	v_cndmask_b32_e64 v56, 0, 1, s[30:31]
	v_cndmask_b32_e32 v54, v56, v54, vcc
	v_and_b32_e32 v54, 1, v54
	v_writelane_b32 v250, s7, 31
	v_cmp_eq_u32_e64 s[6:7], 1, v54
	v_or_b32_e32 v54, 33, v173
	v_cmp_lt_u32_e64 s[30:31], v54, v51
	v_cmp_le_u32_e64 s[34:35], v54, v51
	v_writelane_b32 v250, s6, 32
	v_cndmask_b32_e64 v54, 0, 1, s[30:31]
	v_cndmask_b32_e64 v57, 0, 1, s[34:35]
	v_cndmask_b32_e32 v54, v57, v54, vcc
	v_and_b32_e32 v54, 1, v54
	v_writelane_b32 v250, s7, 33
	v_cmp_eq_u32_e64 s[6:7], 1, v54
	v_or_b32_e32 v54, 34, v173
	v_cmp_lt_u32_e64 s[34:35], v54, v51
	v_cmp_le_u32_e64 s[36:37], v54, v51
	v_writelane_b32 v250, s6, 34
	v_cndmask_b32_e64 v54, 0, 1, s[34:35]
	v_cndmask_b32_e64 v57, 0, 1, s[36:37]
	v_cndmask_b32_e32 v54, v57, v54, vcc
	v_and_b32_e32 v54, 1, v54
	v_writelane_b32 v250, s7, 35
	v_cmp_eq_u32_e64 s[6:7], 1, v54
	v_or_b32_e32 v54, 35, v173
	v_cmp_lt_u32_e64 s[36:37], v54, v51
	v_cmp_le_u32_e64 s[38:39], v54, v51
	v_writelane_b32 v250, s6, 36
	v_cndmask_b32_e64 v51, 0, 1, s[36:37]
	v_cndmask_b32_e64 v54, 0, 1, s[38:39]
	v_cndmask_b32_e32 v51, v54, v51, vcc
	v_and_b32_e32 v51, 1, v51
	v_add3_u32 v182, v47, v48, v28
	v_mad_u32_u24 v47, v166, s73, v52
	v_mad_u32_u24 v48, v166, s73, v53
	v_writelane_b32 v250, s7, 37
	v_cmp_eq_u32_e64 s[6:7], 1, v51
	v_mad_u32_u24 v51, v49, s73, v53
	v_mad_u32_u24 v53, v49, s73, v52
	v_cndmask_b32_e64 v52, 0, 1, vcc
	v_writelane_b32 v250, s6, 38
	v_or_b32_e32 v52, v173, v52
	v_mad_u32_u24 v183, v166, s73, v55
	v_writelane_b32 v250, s7, 39
	v_cmp_gt_u32_e64 s[6:7], v166, v52
	v_or_b32_e32 v52, 2, v173
	v_cmp_lt_u32_e64 s[40:41], v52, v166
	v_cmp_le_u32_e64 s[42:43], v52, v166
	v_writelane_b32 v250, s6, 40
	v_cndmask_b32_e64 v52, 0, 1, s[40:41]
	v_cndmask_b32_e64 v54, 0, 1, s[42:43]
	v_cndmask_b32_e32 v52, v54, v52, vcc
	v_and_b32_e32 v52, 1, v52
	v_writelane_b32 v250, s7, 41
	v_cmp_eq_u32_e64 s[6:7], 1, v52
	v_or_b32_e32 v52, 3, v173
	v_cmp_lt_u32_e64 s[42:43], v52, v166
	v_cmp_le_u32_e64 s[44:45], v52, v166
	v_writelane_b32 v250, s6, 42
	v_cndmask_b32_e64 v52, 0, 1, s[42:43]
	v_cndmask_b32_e64 v54, 0, 1, s[44:45]
	v_cndmask_b32_e32 v52, v54, v52, vcc
	v_and_b32_e32 v52, 1, v52
	v_writelane_b32 v250, s7, 43
	v_cmp_eq_u32_e64 s[6:7], 1, v52
	v_or_b32_e32 v52, 48, v173
	v_cmp_lt_u32_e64 s[44:45], v52, v49
	v_cmp_le_u32_e64 s[46:47], v52, v49
	v_mad_u32_u24 v189, v49, s73, v55
	v_cndmask_b32_e64 v54, 0, 1, s[44:45]
	v_cndmask_b32_e64 v55, 0, 1, s[46:47]
	v_cndmask_b32_e32 v54, v55, v54, vcc
	v_writelane_b32 v250, s6, 44
	v_and_b32_e32 v54, 1, v54
	s_mov_b32 s25, s50
	v_writelane_b32 v250, s7, 45
	v_cmp_eq_u32_e64 s[6:7], 1, v54
	v_or_b32_e32 v54, 49, v173
	v_cmp_lt_u32_e64 s[46:47], v54, v49
	v_cmp_le_u32_e64 s[48:49], v54, v49
	v_writelane_b32 v250, s6, 46
	v_cndmask_b32_e64 v54, 0, 1, s[46:47]
	v_cndmask_b32_e64 v55, 0, 1, s[48:49]
	v_cndmask_b32_e32 v54, v55, v54, vcc
	v_and_b32_e32 v54, 1, v54
	v_writelane_b32 v250, s7, 47
	v_cmp_eq_u32_e64 s[6:7], 1, v54
	v_or_b32_e32 v54, 50, v173
	v_cmp_lt_u32_e64 s[48:49], v54, v49
	s_mov_b32 s24, s51
	v_cmp_le_u32_e64 s[50:51], v54, v49
	v_cndmask_b32_e64 v54, 0, 1, s[48:49]
	v_writelane_b32 v250, s6, 48
	v_cndmask_b32_e64 v55, 0, 1, s[50:51]
	v_cndmask_b32_e32 v54, v55, v54, vcc
	v_and_b32_e32 v54, 1, v54
	v_writelane_b32 v250, s7, 49
	v_cmp_eq_u32_e64 s[6:7], 1, v54
	v_or_b32_e32 v54, 51, v173
	v_cmp_lt_u32_e64 s[50:51], v54, v49
	v_cmp_le_u32_e64 s[52:53], v54, v49
	v_writelane_b32 v250, s6, 50
	v_cndmask_b32_e64 v49, 0, 1, s[50:51]
	v_cndmask_b32_e64 v54, 0, 1, s[52:53]
	v_cndmask_b32_e32 v49, v54, v49, vcc
	v_and_b32_e32 v49, 1, v49
	v_writelane_b32 v250, s7, 51
	v_cmp_eq_u32_e64 s[6:7], 1, v49
	v_lshlrev_b32_e32 v49, 1, v52
	v_add_u32_e32 v57, 0, v28
	v_writelane_b32 v250, s6, 52
	v_lshl_or_b32 v52, s54, 5, v166
	v_mul_u32_u24_e32 v58, 0x90, v52
	v_writelane_b32 v250, s7, 53
	s_movk_i32 s7, 0x9c
	v_or_b32_e32 v52, 16, v52
	v_mad_u32_u24 v60, v166, s7, v57
	s_movk_i32 s7, 0x480
	v_mul_u32_u24_e32 v59, 0x90, v52
	v_mad_u32_u24 v52, v171, s7, 0
	s_and_b32 s7, s24, 0xffffffc0
	s_lshl_b32 s26, s0, 4
	v_add3_u32 v191, v52, s7, v28
	v_lshlrev_b32_e32 v28, 9, v171
	v_or_b32_e32 v168, s26, v166
	s_movk_i32 s6, 0x90
	v_writelane_b32 v250, s24, 54
	v_sub_u32_e32 v28, v52, v28
	v_lshl_add_u32 v62, s25, 5, v28
	v_writelane_b32 v250, s55, 55
	v_mul_lo_u32 v28, v168, s6
	s_add_i32 s6, 0, 0x20400
	s_add_i32 s93, 0, 0x1b800
	s_add_i32 s40, 0, 0x12000
	s_and_b32 s7, s92, 2
	s_add_i32 s24, 0, 0x1dc00
	v_add_u32_e32 v193, s6, v110
	s_add_i32 s6, s26, 64
	s_add_i32 s41, 0, 0x19400
	s_add_i32 s42, 0, 0x17000
	v_writelane_b32 v250, s25, 56
	s_bitcmp1_b32 s25, 0
	v_writelane_b32 v250, s26, 57
	v_or_b32_e32 v73, s26, v173
	s_movk_i32 s43, 0x120
	v_add_u32_e32 v66, s93, v28
	v_or_b32_e32 v52, s6, v166
	v_add_u32_e32 v68, s42, v28
	v_add_u32_e32 v69, s41, v28
	v_lshl_or_b32 v70, s7, 4, v166
	s_cselect_b64 s[62:63], -1, 0
	s_lshl_b32 s6, s7, 10
	v_lshl_or_b32 v169, s0, 8, v188
	s_or_b32 s0, s7, 1
	v_mul_lo_u32 v28, v73, s43
	v_writelane_b32 v250, s54, 58
	s_lshl_b32 s7, s54, 7
	v_add_u32_e32 v192, s24, v110
	s_add_i32 s24, 0, 0x22c00
	v_lshl_or_b32 v71, s0, 4, v166
	s_lshl_b32 s0, s0, 10
	v_add3_u32 v202, v57, v28, s7
	v_lshlrev_b32_e32 v28, 1, v73
	s_mov_b32 s7, 0x1ffffff0
	v_readlane_b32 s26, v250, 19
	v_and_or_b32 v57, v28, s7, v166
	v_readlane_b32 s27, v250, 20
	s_add_u32 s38, s66, 0x1000
	v_add_u32_e32 v203, 0, v28
	v_lshl_add_u64 v[118:119], s[26:27], 0, v[28:29]
	v_lshlrev_b32_e32 v28, 3, v57
	s_addc_u32 s39, s67, 0
	v_add_u32_e32 v114, s6, v169
	v_add_u32_e32 v57, s6, v28
	s_add_u32 s6, s68, 0x800
	s_addc_u32 s7, s69, 0
	v_or_b32_e32 v120, v57, v72
	v_or_b32_e32 v57, 1, v73
	v_cmp_eq_u32_e64 s[52:53], v73, v70
	v_add_u32_e32 v28, s0, v28
	v_writelane_b32 v250, s6, 59
	v_cmp_eq_u32_e32 vcc, v57, v70
	v_cndmask_b32_e64 v122, 0, 1.0, s[52:53]
	v_or_b32_e32 v124, v28, v72
	v_cmp_eq_u32_e64 s[52:53], v73, v71
	v_or_b32_e32 v28, 3, v73
	v_writelane_b32 v250, s7, 60
	s_add_u32 s6, s66, 0x800
	v_cndmask_b32_e64 v123, 0, 1.0, vcc
	v_cmp_eq_u32_e32 vcc, v57, v71
	v_cndmask_b32_e64 v126, 0, 1.0, s[52:53]
	v_or_b32_e32 v57, 2, v73
	v_cmp_eq_u32_e64 s[52:53], v28, v70
	s_addc_u32 s7, s67, 0
	v_mad_u32_u24 v26, v111, s73, 0
	v_lshlrev_b32_e32 v27, 4, v27
	v_mul_lo_u32 v186, v168, s73
	v_mul_lo_u32 v52, v52, s73
	v_cndmask_b32_e64 v127, 0, 1.0, vcc
	v_cmp_eq_u32_e32 vcc, v57, v70
	v_cndmask_b32_e64 v129, 0, 1.0, s[52:53]
	v_cmp_eq_u32_e64 s[52:53], v28, v71
	v_writelane_b32 v250, s6, 61
	v_lshlrev_b32_e32 v28, 5, v0
	v_add_u32_e32 v50, 0xa00, v183
	v_add_u32_e32 v56, 0x1400, v183
	v_add_u32_e32 v55, 0, v186
	v_add_u32_e32 v190, s93, v110
	v_add_u32_e32 v64, s40, v185
	v_add_u32_e32 v65, s40, v186
	v_add_u32_e32 v67, s40, v52
	v_lshlrev_b32_e32 v52, 6, v70
	v_lshlrev_b32_e32 v54, 6, v71
	v_add_u32_e32 v116, s0, v169
	v_cndmask_b32_e64 v128, 0, 1.0, vcc
	v_cmp_eq_u32_e32 vcc, v57, v71
	v_writelane_b32 v250, s7, 62
	s_add_u32 s6, s68, 0x1000
	v_and_b32_e32 v28, 0x3800, v28
	v_add_u32_e32 v206, v26, v27
	v_add_u32_e32 v207, v181, v46
	v_mbcnt_lo_u32_b32 v26, -1, 0
	v_mov_b32_e32 v46, 0
	v_add_u32_e32 v194, s41, v110
	v_add_u32_e32 v195, s40, v110
	v_mul_u32_u24_e32 v196, 0xa0, v70
	v_mul_u32_u24_e32 v197, 0x90, v70
	v_lshl_add_u32 v198, v70, 2, s24
	v_ashrrev_i32_e32 v115, 31, v114
	v_mul_u32_u24_e32 v199, 0xa0, v71
	v_mul_u32_u24_e32 v200, 0x90, v71
	v_lshl_add_u32 v201, v71, 2, s24
	v_ashrrev_i32_e32 v117, 31, v116
	v_lshl_add_u32 v204, v73, 2, s24
	v_ashrrev_i32_e32 v121, 31, v120
	v_ashrrev_i32_e32 v125, 31, v124
	v_cndmask_b32_e64 v131, 0, 1.0, s[52:53]
	v_cndmask_b32_e64 v130, 0, 1.0, vcc
	s_addc_u32 s7, s69, 0
	v_lshl_add_u64 v[132:133], s[70:71], 0, v[28:29]
	s_mov_b32 s34, -1
	s_movk_i32 s71, 0x630
	s_mov_b32 s44, 0x3e0f83e1
	s_movk_i32 s45, 0xfdf0
	s_movk_i32 s46, 0x2940
	s_mov_b32 s47, 0x5040100
	s_mov_b32 s70, 0xbf60033a
	v_mbcnt_hi_u32_b32 v208, -1, v26
	s_add_i32 s48, 0, 0x12280
	s_movk_i32 s49, 0x2600
	v_add_u32_e32 v209, v50, v172
	v_add_u32_e32 v210, v51, v110
	v_add_u32_e32 v211, v53, v110
	v_add_u32_e32 v212, v189, v49
	v_add_u32_e32 v213, v60, v172
	v_add_u32_e32 v214, v62, v61
	v_add_u32_e32 v216, v64, v172
	v_add_u32_e32 v217, v65, v110
	v_lshlrev_b32_e32 v134, 1, v52
	v_add_u32_e32 v218, v68, v110
	v_add_u32_e32 v219, v69, v110
	v_lshlrev_b32_e32 v136, 1, v54
	v_add_u32_e32 v221, v47, v110
	v_add_u32_e32 v222, v48, v110
	v_add_u32_e32 v223, v56, v172
	v_mov_b32_e32 v139, v46
	v_add_u32_e32 v224, v55, v110
	v_add_u32_e32 v225, v190, v58
	v_add_u32_e32 v226, v190, v59
	v_add_u32_e32 v227, v66, v110
	v_add_u32_e32 v228, v67, v110
	s_mov_b32 s51, 0
	v_lshrrev_b32_e32 v26, 3, v0
	v_and_b32_e32 v27, 7, v0
	v_mul_u32_u24_e32 v26, 0x2600, v26
	v_lshl_add_u32 v251, v27, 4, v26
	v_mov_b32_e32 v26, v0
	v_lshrrev_b32_e32 v27, 4, v26
	v_mul_u32_u24_e32 v27, 0x7c2, v27
	v_lshrrev_b32_e32 v27, 16, v27
	v_mul_u32_u24_e32 v28, 0x210, v27
	v_sub_u32_e32 v26, v26, v28
	v_lshrrev_b32_e32 v28, 3, v26
	v_and_b32_e32 v26, 7, v26
	v_mul_u32_u24_e32 v28, 0x2600, v28
	v_lshl_add_u32 v28, v27, 10, v28
	v_lshl_add_u32 v252, v26, 4, v28
	v_add_u32_e32 v26, 0x200, v0
	v_lshrrev_b32_e32 v27, 4, v26
	v_mul_u32_u24_e32 v27, 0x7c2, v27
	v_lshrrev_b32_e32 v27, 16, v27
	v_mul_u32_u24_e32 v28, 0x210, v27
	v_sub_u32_e32 v26, v26, v28
	v_lshrrev_b32_e32 v28, 3, v26
	v_and_b32_e32 v26, 7, v26
	v_mul_u32_u24_e32 v28, 0x2600, v28
	v_lshl_add_u32 v28, v27, 10, v28
	v_lshl_add_u32 v253, v26, 4, v28
	v_add_u32_e32 v26, 0x400, v0
	v_lshrrev_b32_e32 v27, 4, v26
	v_mul_u32_u24_e32 v27, 0x7c2, v27
	v_lshrrev_b32_e32 v27, 16, v27
	v_mul_u32_u24_e32 v28, 0x210, v27
	v_sub_u32_e32 v26, v26, v28
	v_lshrrev_b32_e32 v28, 3, v26
	v_and_b32_e32 v26, 7, v26
	v_mul_u32_u24_e32 v28, 0x2600, v28
	v_lshl_add_u32 v28, v27, 10, v28
	v_lshl_add_u32 v254, v26, 4, v28
	v_add_u32_e32 v26, 0x600, v0
	v_lshrrev_b32_e32 v27, 4, v26
	v_mul_u32_u24_e32 v27, 0x7c2, v27
	v_lshrrev_b32_e32 v27, 16, v27
	v_mul_u32_u24_e32 v28, 0x210, v27
	v_sub_u32_e32 v26, v26, v28
	v_lshrrev_b32_e32 v28, 3, v26
	v_and_b32_e32 v26, 7, v26
	v_mul_u32_u24_e32 v28, 0x2600, v28
	v_lshl_add_u32 v28, v27, 10, v28
	v_lshl_add_u32 v255, v26, 4, v28
	v_mov_b32_e32 v26, v0
	v_cmp_lt_u32_e32 vcc, 0x20f, v26
	s_nop 1
	v_cndmask_b32_e64 v27, 0, 1, vcc
	v_cmp_lt_u32_e32 vcc, 0x41f, v26
	s_nop 1
	v_addc_co_u32_e32 v27, vcc, 0, v27, vcc
	v_mul_u32_u24_e32 v28, 0x210, v27
	v_sub_u32_e32 v28, v26, v28
	v_lshrrev_b32_e32 v28, 3, v28
	v_mul_u32_u24_e32 v28, 0xa0, v28
	v_mul_u32_u24_e32 v27, 0x2940, v27
	v_and_b32_e32 v26, 7, v26
	v_lshlrev_b32_e32 v26, 4, v26
	v_add3_u32 v110, v27, v28, v26
	v_add_u32_e32 v26, 0x200, v0
	v_cmp_lt_u32_e32 vcc, 0x20f, v26
	s_nop 1
	v_cndmask_b32_e64 v27, 0, 1, vcc
	v_cmp_lt_u32_e32 vcc, 0x41f, v26
	s_nop 1
	v_addc_co_u32_e32 v27, vcc, 0, v27, vcc
	v_mul_u32_u24_e32 v28, 0x210, v27
	v_sub_u32_e32 v28, v26, v28
	v_lshrrev_b32_e32 v28, 3, v28
	v_mul_u32_u24_e32 v28, 0xa0, v28
	v_mul_u32_u24_e32 v27, 0x2940, v27
	v_and_b32_e32 v26, 7, v26
	v_lshlrev_b32_e32 v26, 4, v26
	v_add3_u32 v111, v27, v28, v26
	v_add_u32_e32 v26, 0x400, v0
	v_cmp_lt_u32_e32 vcc, 0x20f, v26
	s_nop 1
	v_cndmask_b32_e64 v27, 0, 1, vcc
	v_cmp_lt_u32_e32 vcc, 0x41f, v26
	s_nop 1
	v_addc_co_u32_e32 v27, vcc, 0, v27, vcc
	v_mul_u32_u24_e32 v28, 0x210, v27
	v_sub_u32_e32 v28, v26, v28
	v_lshrrev_b32_e32 v28, 3, v28
	v_mul_u32_u24_e32 v28, 0xa0, v28
	v_mul_u32_u24_e32 v27, 0x2940, v27
	v_and_b32_e32 v26, 7, v26
	v_lshlrev_b32_e32 v26, 4, v26
	v_add3_u32 v166, v27, v28, v26
	v_add_u32_e32 v26, 0x600, v0
	v_cmp_lt_u32_e32 vcc, 0x20f, v26
	s_nop 1
	v_cndmask_b32_e64 v27, 0, 1, vcc
	v_cmp_lt_u32_e32 vcc, 0x41f, v26
	s_nop 1
	v_addc_co_u32_e32 v27, vcc, 0, v27, vcc
	v_mul_u32_u24_e32 v28, 0x210, v27
	v_sub_u32_e32 v28, v26, v28
	v_lshrrev_b32_e32 v28, 3, v28
	v_mul_u32_u24_e32 v28, 0xa0, v28
	v_mul_u32_u24_e32 v27, 0x2940, v27
	v_and_b32_e32 v26, 7, v26
	v_lshlrev_b32_e32 v26, 4, v26
	v_add3_u32 v168, v27, v28, v26
	v_lshrrev_b32_e32 v26, 5, v0
	v_and_b32_e32 v27, 31, v0
	v_mul_u32_u24_e32 v26, 0x280, v26
	v_lshlrev_b32_e32 v27, 2, v27
	v_add_u32_e32 v169, v26, v27
	v_add_u32_e32 v169, 0x28a0, v169
	v_sub_u32_e32 v170, v27, v26
	v_add_u32_e32 v170, 0x5140, v170
	v_add_u32_e32 v171, 0x2600, v251
	v_add_u32_e32 v173, 0x4c00, v251
	s_branch .LBB0_295

.LBB0_342:
	s_or_b64 exec, exec, s[24:25]
	v_lshlrev_b32_e32 v28, 2, v47
	s_movk_i32 s25, 0xff60
	s_and_b64 vcc, s[54:55], exec
	s_cselect_b32 s24, s25, 0xa0
	v_cndmask_b32_e64 v70, v169, v170, s[54:55]
	v_add_u32_e32 v71, s24, v70
	v_add_u32_e32 v72, s24, v71
	v_add_u32_e32 v73, s24, v72
	v_add_u32_e32 v74, s24, v73
	v_add_u32_e32 v75, s24, v74
	ds_read_b32 v150, v70 offset:42848
	ds_read_b32 v151, v71 offset:42848
	ds_read_b32 v141, v72 offset:42848
	ds_read_b32 v240, v73 offset:42848
	ds_read_b32 v238, v74 offset:42848
	ds_read_b32 v236, v75 offset:42848
	ds_read_b32 v140, v70 offset:53408
	ds_read_b32 v154, v71 offset:53408
	ds_read_b32 v155, v72 offset:53408
	ds_read_b32 v239, v73 offset:53408
	ds_read_b32 v237, v74 offset:53408
	ds_read_b32 v235, v75 offset:53408
	ds_read_b32 v137, v70 offset:63968
	ds_read_b32 v229, v71 offset:63968
	ds_read_b32 v230, v72 offset:63968
	ds_read_b32 v232, v73 offset:63968
	ds_read_b32 v233, v74 offset:63968
	ds_read_b32 v231, v75 offset:63968
	v_lshl_add_u32 v67, v66, 2, 0
	s_waitcnt lgkmcnt(0)
	s_barrier
	v_add_u32_e32 v67, 0x8000, v67
	ds_read2_b64 v[90:93], v67 offset1:32
	ds_read2_b64 v[86:89], v67 offset0:64 offset1:96
	ds_read2_b64 v[82:85], v67 offset0:128 offset1:160
	ds_read2_b64 v[78:81], v67 offset0:192 offset1:224
	s_add_i32 vcc_hi, s51, 1
	s_cmp_ge_u32 vcc_hi, s72
	s_cbranch_scc1 .Lel_skip
	s_add_i32 vcc_hi, s0, 1
	s_bfe_u32 s36, vcc_hi, 0x60001
	s_add_i32 s37, s36, -1
	s_cmp_lt_u32 s37, 62
	s_cbranch_scc0 .Lel_skip
	s_ashr_i32 vcc_lo, vcc_hi, 10
	s_lshl_b32 vcc_lo, vcc_lo, 12
	s_lshl_b32 s36, s36, 6
	s_add_i32 vcc_lo, vcc_lo, s36
	s_mul_i32 vcc_lo, vcc_lo, 0x2600
	s_add_u32 s30, s64, vcc_lo
	s_addc_u32 s31, s65, 0
	s_add_u32 s30, s30, 0xffffda00
	s_addc_u32 s31, s31, -1
	s_bfe_u32 vcc_lo, vcc_hi, 0x30007
	s_lshl_b32 vcc_lo, vcc_lo, 7
	s_add_u32 s36, s30, vcc_lo
	s_addc_u32 s37, s31, 0
	s_and_b32 vcc_lo, vcc_hi, 1
	s_lshl_b32 vcc_lo, vcc_lo, 7
	s_addk_i32 vcc_lo, 0x1000
	s_add_u32 s30, s30, vcc_lo
	s_addc_u32 s31, s31, 0
	global_load_dwordx4 v[2:5], v171, s[30:31]
	global_load_dwordx4 v[10:13], v251, s[30:31]
	global_load_dwordx4 v[6:9], v173, s[30:31]
	global_load_dwordx4 v[14:17], v171, s[30:31] offset:256
	global_load_dwordx4 v[22:25], v251, s[30:31] offset:256
	global_load_dwordx4 v[18:21], v173, s[30:31] offset:256
	global_load_dwordx4 v[30:33], v252, s[36:37]
	global_load_dwordx4 v[34:37], v253, s[36:37]
	global_load_dwordx4 v[38:41], v254, s[36:37]
	v_cmp_gt_i32_e32 vcc, 48, v0
	s_and_saveexec_b64 vcc, vcc
	s_cbranch_execz .Lel_s3
	global_load_dwordx4 v[42:45], v255, s[36:37]
.Lel_s3:
	s_or_b64 exec, exec, vcc
.Lel_skip:
	v_cmp_eq_u32_e32 vcc, 15, v135
	s_and_saveexec_b64 s[24:25], vcc
	s_cbranch_execz .LBB0_344
	s_waitcnt lgkmcnt(3)
	v_pk_add_f32 v[68:69], v[90:91], 0 op_sel_hi:[1,0]
	v_mov_b32_e32 v67, v66
	v_pk_add_f32 v[68:69], v[68:69], v[92:93]
	s_waitcnt lgkmcnt(2)
	v_pk_add_f32 v[68:69], v[68:69], v[86:87]
	v_lshl_add_u32 v67, v67, 2, 0
	v_pk_add_f32 v[68:69], v[68:69], v[88:89]
	v_add_u32_e32 v67, 0x22c00, v67
	s_waitcnt lgkmcnt(1)
	v_pk_add_f32 v[68:69], v[68:69], v[82:83]
	s_nop 0
	v_pk_add_f32 v[68:69], v[68:69], v[84:85]
	s_waitcnt lgkmcnt(0)
	v_pk_add_f32 v[68:69], v[68:69], v[78:79]
	s_nop 0
	v_pk_add_f32 v[68:69], v[68:69], v[80:81]
	s_nop 0
	v_exp_f32_e32 v68, v68
	v_exp_f32_e32 v69, v69
	ds_write_b64 v67, v[68:69]

.LBB0_352:
	s_or_b64 exec, exec, s[28:29]
	v_add_f32_e32 v87, v87, v100
	v_cndmask_b32_e64 v49, v69, v67, s[54:55]
	v_cndmask_b32_e64 v48, v68, v66, s[54:55]
	v_max_f32_e32 v87, 0x179abe15, v87
	v_cndmask_b32_e64 v67, v67, v69, s[54:55]
	v_cndmask_b32_e64 v66, v66, v68, s[54:55]
	v_pk_add_f32 v[68:69], v[48:49], 1.0 op_sel_hi:[1,0] neg_lo:[1,0] neg_hi:[1,0]
	v_rsq_f32_e32 v100, v87
	v_pk_add_f32 v[68:69], v[68:69], v[66:67] neg_lo:[0,1] neg_hi:[0,1]
	v_lshlrev_b32_e32 v76, 16, v233
	v_and_b32_e32 v77, 0xffff0000, v233
	v_lshlrev_b32_e32 v70, 16, v232
	v_and_b32_e32 v71, 0xffff0000, v232
	v_pk_mul_f32 v[104:105], v[68:69], v[76:77]
	v_lshlrev_b32_e32 v102, 16, v231
	v_and_b32_e32 v103, 0xffff0000, v231
	v_pk_fma_f32 v[104:105], v[48:49], v[70:71], v[104:105]
	v_pk_mul_f32 v[98:99], v[98:99], v[100:101] op_sel_hi:[1,0]
	v_pk_fma_f32 v[102:103], v[66:67], v[102:103], v[104:105]
	v_lshlrev_b32_e32 v100, 16, v230
	v_and_b32_e32 v101, 0xffff0000, v230
	v_pk_mul_f32 v[104:105], v[68:69], v[70:71]
	v_pk_mul_f32 v[106:107], v[68:69], v[100:101]
	v_pk_fma_f32 v[104:105], v[48:49], v[100:101], v[104:105]
	v_pk_add_f32 v[26:27], v[26:27], v[80:81]
	v_pk_fma_f32 v[76:77], v[66:67], v[76:77], v[104:105]
	v_lshlrev_b32_e32 v104, 16, v229
	v_and_b32_e32 v105, 0xffff0000, v229
	v_pk_fma_f32 v[106:107], v[48:49], v[104:105], v[106:107]
	v_pk_mul_f32 v[68:69], v[68:69], v[104:105]
	v_pk_fma_f32 v[70:71], v[66:67], v[70:71], v[106:107]
	v_lshlrev_b32_e32 v106, 16, v137
	v_and_b32_e32 v107, 0xffff0000, v137
	v_pk_fma_f32 v[48:49], v[48:49], v[106:107], v[68:69]
	v_pk_mul_f32 v[68:69], v[94:95], v[98:99]
	v_pk_fma_f32 v[48:49], v[66:67], v[100:101], v[48:49]
	v_exp_f32_e32 v66, v26
	v_exp_f32_e32 v67, v27
	v_exp_f32_e64 v26, -v26
	v_exp_f32_e64 v27, -v27
	v_pk_mul_f32 v[96:97], v[96:97], v[98:99]
	v_pk_mul_f32 v[66:67], v[66:67], v[90:91]
	v_cvt_pk_bf16_f32 v68, v68, v69
	v_pk_mul_f32 v[74:75], v[26:27], v[74:75]
	v_cvt_pk_bf16_f32 v66, v66, v67
	v_add_u32_e32 v28, 64, v28
	s_add_i32 s26, 0, 0x14800
	v_pk_mul_f32 v[26:27], v[26:27], v[96:97]
	ds_write2st64_b32 v28, v68, v66 offset0:209 offset1:249
	v_cvt_pk_bf16_f32 v28, v74, v75
	v_add_u32_e32 v66, s40, v86
	ds_write_b32 v66, v28 offset:320
	v_cvt_pk_bf16_f32 v28, v26, v27
	v_add_u32_e32 v66, s26, v86
	ds_write_b32 v66, v28 offset:320
	v_lshlrev_b32_e32 v28, 3, v135
	v_add_u32_e32 v68, s42, v28
	v_cvt_pk_bf16_f32 v66, v78, v84
	v_cvt_pk_bf16_f32 v67, v92, v74
	v_mad_u32_u24 v69, v47, s43, v68
	ds_write_b64 v69, v[66:67]
	v_mad_u32_u24 v69, v47, s43, v220
	v_cvt_pk_bf16_f32 v66, v79, v85
	v_cvt_pk_bf16_f32 v67, v93, v75
	v_add_u32_e32 v68, v68, v69
	ds_write_b64 v68, v[66:67]
	v_add_u32_e32 v68, s41, v28
	v_cvt_pk_bf16_f32 v66, v72, v82
	v_cvt_pk_bf16_f32 v67, v88, v26
	v_mad_u32_u24 v26, v47, s43, v68
	ds_write_b64 v26, v[66:67]
	v_cvt_pk_bf16_f32 v26, v73, v83
	v_cvt_pk_bf16_f32 v27, v89, v27
	v_add_u32_e32 v66, v68, v69
	v_add_u32_e32 v28, s93, v28
	s_add_i32 s51, s51, 1
	ds_write_b64 v66, v[26:27]
	v_cvt_pk_bf16_f32 v26, v48, v70
	v_cvt_pk_bf16_f32 v27, v76, v102
	v_mad_u32_u24 v47, v47, s43, v28
	s_cmp_ge_u32 s51, s72
	ds_write_b64 v47, v[26:27]
	v_cvt_pk_bf16_f32 v26, v49, v71
	v_cvt_pk_bf16_f32 v27, v77, v103
	v_add_u32_e32 v28, v28, v69
	ds_write_b64 v28, v[26:27]
	s_cbranch_scc1 .LBB0_378
	s_add_i32 s0, s0, 1
	s_bfe_u32 s36, s0, 0x60001
	s_add_i32 s37, s36, -1
	s_cmp_lt_u32 s37, 62
	s_cbranch_scc0 .Lrwl_slow
	s_branch .LBB0_378
